# attention: 66 packed v_pk_fma_f32 (QK accumulator init beside the MFMAs) split into single v_fma_f32 pairs (strategy 7: packed vs scalar fp32 beside MFMAs)
# baseline (speedup 1.0000x reference)
.LBB0_321:
	s_sub_i32 s23, s58, 64
	v_cvt_f32_u32_e32 v0, s23
	v_fma_f32 v0, v224, v0, v208
	v_sub_f32_e32 v0, v0, v238
	v_fma_f32 v128, 0, v224, v0
	v_add_f32_e32 v129, v224, v0
	v_fma_f32 v131, v225, s7, v0
	v_fma_f32 v130, v224, s6, v0
	v_fma_f32 v133, v225, s9, v0
	v_fma_f32 v132, v224, s8, v0
	v_fma_f32 v135, v225, s11, v0
	v_fma_f32 v134, v224, s10, v0
	v_fma_f32 v137, v225, s13, v0
	v_fma_f32 v136, v224, s12, v0
	v_fma_f32 v139, v225, s15, v0
	v_fma_f32 v138, v224, s14, v0
	v_fma_f32 v141, v225, s17, v0
	v_fma_f32 v140, v224, s16, v0
	v_fma_f32 v143, v225, s19, v0
	v_fma_f32 v142, v224, s18, v0
	s_lshl_b32 s22, s22, 1
	v_add_u32_e32 v216, s22, v211
	ds_read_b64_tr_b16 v[6:7], v216 offset:24576
	ds_read_b64_tr_b16 v[8:9], v216 offset:25088
	v_add_f32_e32 v2, v96, v97
	v_add_f32_e32 v2, v98, v2
	v_add_f32_e32 v2, v99, v2
	v_add_f32_e32 v2, v100, v2
	v_add_f32_e32 v10, v101, v2
	v_cvt_pk_bf16_f32 v168, v96, v97
	v_cvt_pk_bf16_f32 v169, v98, v99
	ds_read_b64_tr_b16 v[2:3], v216 offset:28672
	ds_read_b64_tr_b16 v[4:5], v216 offset:29184
	s_waitcnt lgkmcnt(11)
	v_mfma_f32_32x32x16_bf16 v[128:143], v[204:207], v[172:175], v[128:143]
	v_add_f32_e32 v0, v210, v0
	v_fma_f32 v112, 0, v224, v0
	v_add_f32_e32 v113, v224, v0
	v_fma_f32 v114, v224, s6, v0
	v_fma_f32 v115, v225, s7, v0
	v_fma_f32 v117, v225, s9, v0
	v_fma_f32 v116, v224, s8, v0
	v_fma_f32 v119, v225, s11, v0
	v_fma_f32 v118, v224, s10, v0
	v_fma_f32 v121, v225, s13, v0
	v_fma_f32 v120, v224, s12, v0
	v_fma_f32 v123, v225, s15, v0
	v_fma_f32 v122, v224, s14, v0
	v_fma_f32 v125, v225, s17, v0
	v_fma_f32 v124, v224, s16, v0
	v_fma_f32 v127, v225, s19, v0
	v_fma_f32 v126, v224, s18, v0
	s_waitcnt lgkmcnt(10)
	s_nop 0
	v_mfma_f32_32x32x16_bf16 v[112:127], v[200:203], v[172:175], v[112:127]
	v_add_f32_e32 v0, v102, v10
	v_add_f32_e32 v0, v103, v0
	v_add_f32_e32 v0, v104, v0
	v_add_f32_e32 v0, v105, v0
	v_cvt_pk_bf16_f32 v170, v100, v101
	v_cvt_pk_bf16_f32 v171, v102, v103
	ds_read_b64_tr_b16 v[10:11], v216 offset:25600
	ds_read_b64_tr_b16 v[12:13], v216 offset:26112
	s_waitcnt lgkmcnt(11)
	v_mfma_f32_32x32x16_bf16 v[128:143], v[196:199], v[160:163], v[128:143]
	v_add_f32_e32 v0, v106, v0
	v_add_f32_e32 v0, v107, v0
	v_add_f32_e32 v0, v108, v0
	v_add_f32_e32 v0, v109, v0
	v_cvt_pk_bf16_f32 v164, v104, v105
	v_cvt_pk_bf16_f32 v165, v106, v107
	ds_read_b64_tr_b16 v[96:97], v216 offset:29696
	ds_read_b64_tr_b16 v[98:99], v216 offset:30208
	s_waitcnt lgkmcnt(12)
	v_mfma_f32_32x32x16_bf16 v[112:127], v[192:195], v[160:163], v[112:127]
	v_add_f32_e32 v0, v110, v0
	v_add_f32_e32 v0, v111, v0
	v_add_f32_e32 v0, v80, v0
	v_add_f32_e32 v0, v81, v0
	v_cvt_pk_bf16_f32 v166, v108, v109
	v_cvt_pk_bf16_f32 v167, v110, v111
	ds_read_b64_tr_b16 v[100:101], v216 offset:26624
	ds_read_b64_tr_b16 v[102:103], v216 offset:27136
	s_waitcnt lgkmcnt(13)
	v_mfma_f32_32x32x16_bf16 v[128:143], v[188:191], v[148:151], v[128:143]
	v_add_f32_e32 v0, v82, v0
	v_add_f32_e32 v0, v83, v0
	v_add_f32_e32 v0, v84, v0
	v_add_f32_e32 v0, v85, v0
	v_cvt_pk_bf16_f32 v156, v80, v81
	v_cvt_pk_bf16_f32 v157, v82, v83
	ds_read_b64_tr_b16 v[80:81], v216 offset:30720
	ds_read_b64_tr_b16 v[82:83], v216 offset:31232
	s_waitcnt lgkmcnt(14)
	v_mfma_f32_32x32x16_bf16 v[112:127], v[184:187], v[148:151], v[112:127]
	v_add_f32_e32 v0, v86, v0
	v_add_f32_e32 v0, v87, v0
	v_add_f32_e32 v0, v88, v0
	v_add_f32_e32 v0, v89, v0
	v_cvt_pk_bf16_f32 v158, v84, v85
	v_cvt_pk_bf16_f32 v159, v86, v87
	ds_read_b64_tr_b16 v[84:85], v216 offset:27648
	ds_read_b64_tr_b16 v[86:87], v216 offset:28160
	s_waitcnt lgkmcnt(14)
	v_mfma_f32_32x32x16_bf16 v[128:143], v[180:183], v[144:147], v[128:143]
	v_add_f32_e32 v0, v90, v0
	v_add_f32_e32 v0, v91, v0
	v_add_f32_e32 v0, v92, v0
	v_add_f32_e32 v0, v93, v0
	v_cvt_pk_bf16_f32 v152, v88, v89
	v_cvt_pk_bf16_f32 v153, v90, v91
	ds_read_b64_tr_b16 v[88:89], v216 offset:31744
	ds_read_b64_tr_b16 v[90:91], v216 offset:32256
	v_mfma_f32_32x32x16_bf16 v[112:127], v[176:179], v[144:147], v[112:127]
	v_add_f32_e32 v0, v94, v0
	v_add_f32_e32 v0, v95, v0
	v_add_f32_e32 v0, 0, v0
	v_cvt_pk_bf16_f32 v154, v92, v93
	v_cvt_pk_bf16_f32 v155, v94, v95
	v_lshl_add_u64 v[200:201], v[226:227], 0, s[94:95]
	s_mov_b64 s[22:23], 0x320000
	v_lshl_add_u64 v[14:15], v[200:201], 0, s[22:23]
	s_add_i32 s22, s80, s82
	s_mov_b32 s23, m0
	s_mov_b32 m0, s22
	s_nop 0
	global_load_lds_dwordx4 v[14:15], off
	s_mov_b32 m0, s23
	v_lshl_add_u64 v[14:15], v[230:231], 0, s[94:95]
	s_mov_b64 s[22:23], 0x1cf92400
	v_lshl_add_u64 v[92:93], v[14:15], 0, s[22:23]
	s_lshl_b32 s22, s88, 1
	s_add_i32 s34, s22, s81
	s_mov_b32 s22, m0
	s_mov_b32 m0, s34
	s_nop 0
	global_load_lds_dwordx4 v[92:93], off
	s_mov_b32 m0, s22
	s_mov_b64 s[22:23], 0x1cf92480
	v_lshl_add_u64 v[92:93], v[14:15], 0, s[22:23]
	s_add_i32 s22, s34, 0x2000
	s_mov_b32 s23, m0
	s_mov_b32 m0, s22
	s_nop 0
	global_load_lds_dwordx4 v[92:93], off
	s_mov_b32 m0, s23
	v_max_f32_e32 v92, v129, v129
	v_max_f32_e32 v93, v128, v128
	v_max_f32_e32 v92, v93, v92
	v_max3_f32 v93, v130, v131, v113
	v_max3_f32 v92, v92, v112, v114
	v_max3_f32 v92, v92, v115, v132
	v_max3_f32 v93, v93, v134, v135
	v_max3_f32 v92, v92, v133, v116
	v_max3_f32 v93, v93, v118, v119
	v_max3_f32 v92, v92, v117, v136
	v_max3_f32 v93, v93, v138, v139
	v_max3_f32 v92, v92, v137, v120
	v_max3_f32 v93, v93, v122, v123
	v_max3_f32 v92, v92, v121, v140
	v_max3_f32 v93, v93, v142, v143
	v_max3_f32 v92, v92, v141, v124
	v_max3_f32 v93, v93, v126, v127
	v_max3_f32 v92, v92, v125, v93
	v_mov_b32_e32 v93, v92
	s_nop 1
	v_permlane32_swap_b32_e32 v92, v93
	v_max_f32_e32 v93, v93, v93
	v_max_f32_e32 v92, v92, v92
	v_max_f32_e32 v92, v92, v93
	v_cmp_lt_f32_e32 vcc, s69, v92
	s_cmp_lg_u64 vcc, 0
	v_add_f32_e32 v0, v239, v0
	s_cselect_b64 s[34:35], -1, 0
	s_cbranch_vccnz .LBB0_329

.LBB0_324:
	s_add_i32 s22, s88, 0x2000
	v_cvt_f32_u32_e32 v80, s58
	v_fma_f32 v80, v224, v80, v208
	v_sub_f32_e32 v80, v80, v238
	v_fma_f32 v96, 0, v224, v80
	v_add_f32_e32 v97, v224, v80
	v_fma_f32 v99, v225, s7, v80
	v_fma_f32 v98, v224, s6, v80
	v_fma_f32 v101, v225, s9, v80
	v_fma_f32 v100, v224, s8, v80
	v_fma_f32 v103, v225, s11, v80
	v_fma_f32 v102, v224, s10, v80
	v_fma_f32 v105, v225, s13, v80
	v_fma_f32 v104, v224, s12, v80
	v_fma_f32 v107, v225, s15, v80
	v_fma_f32 v106, v224, s14, v80
	v_fma_f32 v109, v225, s17, v80
	v_fma_f32 v108, v224, s16, v80
	v_fma_f32 v111, v225, s19, v80
	v_fma_f32 v110, v224, s18, v80
	s_lshl_b32 s23, s80, 1
	v_add_u32_e32 v202, s23, v211
	ds_read_b64_tr_b16 v[196:197], v202 offset:24576
	ds_read_b64_tr_b16 v[198:199], v202 offset:25088
	v_add_f32_e32 v81, v128, v129
	v_add_f32_e32 v81, v130, v81
	v_add_f32_e32 v81, v131, v81
	v_add_f32_e32 v81, v132, v81
	v_add_f32_e32 v152, v133, v81
	v_cvt_pk_bf16_f32 v168, v128, v129
	v_cvt_pk_bf16_f32 v169, v130, v131
	ds_read_b64_tr_b16 v[128:129], v202 offset:28672
	ds_read_b64_tr_b16 v[130:131], v202 offset:29184
	s_waitcnt lgkmcnt(11)
	v_mfma_f32_32x32x16_bf16 v[96:111], v[192:195], v[172:175], v[96:111]
	v_add_f32_e32 v94, v210, v80
	s_cmpk_lg_i32 s88, 0x4000
	v_fma_f32 v80, 0, v224, v94
	v_add_f32_e32 v81, v224, v94
	v_fma_f32 v82, v224, s6, v94
	v_fma_f32 v83, v225, s7, v94
	v_fma_f32 v85, v225, s9, v94
	v_fma_f32 v84, v224, s8, v94
	v_fma_f32 v87, v225, s11, v94
	v_fma_f32 v86, v224, s10, v94
	v_fma_f32 v89, v225, s13, v94
	v_fma_f32 v88, v224, s12, v94
	v_fma_f32 v91, v225, s15, v94
	v_fma_f32 v90, v224, s14, v94
	v_fma_f32 v93, v225, s17, v94
	v_fma_f32 v92, v224, s16, v94
	v_fma_f32 v95, v225, s19, v94
	v_fma_f32 v94, v224, s18, v94
	s_cselect_b32 s80, s22, 0
	s_waitcnt lgkmcnt(10)
	v_mfma_f32_32x32x16_bf16 v[80:95], v[188:191], v[172:175], v[80:95]
	v_add_f32_e32 v152, v134, v152
	v_add_f32_e32 v152, v135, v152
	v_add_f32_e32 v152, v136, v152
	v_add_f32_e32 v152, v137, v152
	v_cvt_pk_bf16_f32 v170, v132, v133
	v_cvt_pk_bf16_f32 v171, v134, v135
	ds_read_b64_tr_b16 v[132:133], v202 offset:25600
	ds_read_b64_tr_b16 v[134:135], v202 offset:26112
	s_waitcnt lgkmcnt(11)
	v_mfma_f32_32x32x16_bf16 v[96:111], v[184:187], v[160:163], v[96:111]
	v_add_f32_e32 v152, v138, v152
	v_add_f32_e32 v152, v139, v152
	v_add_f32_e32 v152, v140, v152
	v_add_f32_e32 v152, v141, v152
	v_cvt_pk_bf16_f32 v164, v136, v137
	v_cvt_pk_bf16_f32 v165, v138, v139
	ds_read_b64_tr_b16 v[136:137], v202 offset:29696
	ds_read_b64_tr_b16 v[138:139], v202 offset:30208
	s_waitcnt lgkmcnt(12)
	v_mfma_f32_32x32x16_bf16 v[80:95], v[180:183], v[160:163], v[80:95]
	v_add_f32_e32 v152, v142, v152
	v_add_f32_e32 v152, v143, v152
	v_add_f32_e32 v152, v112, v152
	v_add_f32_e32 v152, v113, v152
	v_cvt_pk_bf16_f32 v166, v140, v141
	v_cvt_pk_bf16_f32 v167, v142, v143
	ds_read_b64_tr_b16 v[140:141], v202 offset:26624
	ds_read_b64_tr_b16 v[142:143], v202 offset:27136
	s_waitcnt lgkmcnt(13)
	v_mfma_f32_32x32x16_bf16 v[96:111], v[176:179], v[148:151], v[96:111]
	v_add_f32_e32 v152, v114, v152
	v_add_f32_e32 v152, v115, v152
	v_add_f32_e32 v152, v116, v152
	v_add_f32_e32 v152, v117, v152
	v_cvt_pk_bf16_f32 v156, v112, v113
	v_cvt_pk_bf16_f32 v157, v114, v115
	ds_read_b64_tr_b16 v[112:113], v202 offset:30720
	ds_read_b64_tr_b16 v[114:115], v202 offset:31232
	s_waitcnt lgkmcnt(14)
	v_mfma_f32_32x32x16_bf16 v[80:95], v[10:13], v[148:151], v[80:95]
	v_add_f32_e32 v10, v118, v152
	v_add_f32_e32 v10, v119, v10
	v_add_f32_e32 v10, v120, v10
	v_add_f32_e32 v152, v121, v10
	v_cvt_pk_bf16_f32 v158, v116, v117
	v_cvt_pk_bf16_f32 v159, v118, v119
	ds_read_b64_tr_b16 v[10:11], v202 offset:27648
	ds_read_b64_tr_b16 v[12:13], v202 offset:28160
	s_waitcnt lgkmcnt(14)
	v_mfma_f32_32x32x16_bf16 v[96:111], v[6:9], v[144:147], v[96:111]
	v_add_f32_e32 v6, v122, v152
	v_add_f32_e32 v6, v123, v6
	v_add_f32_e32 v6, v124, v6
	v_add_f32_e32 v116, v125, v6
	v_cvt_pk_bf16_f32 v152, v120, v121
	v_cvt_pk_bf16_f32 v153, v122, v123
	ds_read_b64_tr_b16 v[6:7], v202 offset:31744
	ds_read_b64_tr_b16 v[8:9], v202 offset:32256
	v_mfma_f32_32x32x16_bf16 v[80:95], v[2:5], v[144:147], v[80:95]
	v_add_f32_e32 v2, v126, v116
	v_add_f32_e32 v2, v127, v2
	v_add_f32_e32 v4, 0, v2
	v_cvt_pk_bf16_f32 v154, v124, v125
	v_cvt_pk_bf16_f32 v155, v126, v127
	s_mov_b64 s[22:23], 0x3e8000
	v_lshl_add_u64 v[2:3], v[200:201], 0, s[22:23]
	s_add_i32 s22, s88, s82
	s_mov_b32 s23, m0
	s_mov_b32 m0, s22
	s_nop 0
	global_load_lds_dwordx4 v[2:3], off
	s_mov_b32 m0, s23
	s_mov_b64 s[22:23], 0x1d05a400
	v_lshl_add_u64 v[2:3], v[14:15], 0, s[22:23]
	s_lshl_b32 s22, s80, 1
	s_add_i32 s34, s22, s81
	s_mov_b32 s22, m0
	s_mov_b32 m0, s34
	s_nop 0
	global_load_lds_dwordx4 v[2:3], off
	s_mov_b32 m0, s22
	s_mov_b64 s[22:23], 0x1d05a480
	v_lshl_add_u64 v[2:3], v[14:15], 0, s[22:23]
	s_add_i32 s22, s34, 0x2000
	s_mov_b32 s23, m0
	s_mov_b32 m0, s22
	s_nop 0
	global_load_lds_dwordx4 v[2:3], off
	s_mov_b32 m0, s23
	v_max_f32_e32 v2, v97, v97
	v_max_f32_e32 v3, v96, v96
	v_max_f32_e32 v2, v3, v2
	v_max3_f32 v3, v98, v99, v81
	v_max3_f32 v2, v2, v80, v82
	v_max3_f32 v2, v2, v83, v100
	v_max3_f32 v3, v3, v102, v103
	v_max3_f32 v2, v2, v101, v84
	v_max3_f32 v3, v3, v86, v87
	v_max3_f32 v2, v2, v85, v104
	v_max3_f32 v3, v3, v106, v107
	v_max3_f32 v2, v2, v105, v88
	v_max3_f32 v3, v3, v90, v91
	v_max3_f32 v2, v2, v89, v108
	v_max3_f32 v3, v3, v110, v111
	v_max3_f32 v2, v2, v109, v92
	v_max3_f32 v3, v3, v94, v95
	v_add_f32_e32 v239, v0, v4
	v_max3_f32 v0, v2, v93, v3
	v_mov_b32_e32 v2, v0
	s_nop 1
	v_permlane32_swap_b32_e32 v0, v2
	v_max_f32_e32 v2, v2, v2
	v_max_f32_e32 v0, v0, v0
	v_max_f32_e32 v0, v0, v2
	v_cmp_lt_f32_e32 vcc, s69, v0
	s_cmp_lg_u64 vcc, 0
	s_cselect_b64 s[34:35], -1, 0
	s_cbranch_vccnz .LBB0_332

;   #define RESC() do{ if(resc){ asm volatile("s_waitcnt lgkmcnt(0)":::"memory"); \
;       _Pragma("unroll") for(int d_=0;d_<4;++d_) _Pragma("unroll") for(int r=0;r<16;++r)o[d_][r]*=wsf[crow(r,hi)]; } }while(0)
;   #define ROT() do{sl_prev=sl_cur;sl_cur=sl_next;sl_next=(sl_next==(NSLOT-1)*SLOTB)?0:sl_next+SLOTB;}while(0)
;   #define ENDW(tt) do{ if((tt)+3<NT){WAIT_BAR(3);} else if((tt)+2<NT){WAIT_BAR(2);} else {WAIT_BAR(0);} }while(0)
; template<int THRL> __device__ __forceinline__ void attn_unit(int b,int qb,int T0,const bf16*Q,const bf16*__restrict__ K,const bf16*__restrict__ V,float*Dg,float cs,float lam,char*shm){
;     ...
;   for(;t+1<NT;t+=2){
;     STEP(pB0,pB1,pA0,pA1,t,(t+3<NT),(t+1<NT),(t+1<NT));       ENDW(t);   RESC(); ROT();
;     STEP(pA0,pA1,pB0,pB1,t+1,(t+4<NT),(t+2<NT),(t+2<NT));     ENDW(t+1); RESC(); ROT();
.LBB0_341:
	s_add_i32 s48, s89, s86
	v_cvt_f32_u32_e32 v2, s48
	v_fma_f32 v2, v224, v2, v208
	v_sub_f32_e32 v10, v2, v238
	v_fma_f32 v128, 0, v224, v10
	v_add_f32_e32 v129, v224, v10
	v_fma_f32 v131, v225, s7, v10
	v_fma_f32 v130, v224, s6, v10
	v_fma_f32 v133, v225, s9, v10
	v_fma_f32 v132, v224, s8, v10
	v_fma_f32 v135, v225, s11, v10
	v_fma_f32 v134, v224, s10, v10
	v_fma_f32 v137, v225, s13, v10
	v_fma_f32 v136, v224, s12, v10
	v_fma_f32 v139, v225, s15, v10
	v_fma_f32 v138, v224, s14, v10
	v_fma_f32 v141, v225, s17, v10
	v_fma_f32 v140, v224, s16, v10
	v_fma_f32 v143, v225, s19, v10
	v_fma_f32 v142, v224, s18, v10
	s_lshl_b32 s22, s88, 1
	v_add_u32_e32 v230, s22, v211
	ds_read_b64_tr_b16 v[6:7], v230 offset:24576
	ds_read_b64_tr_b16 v[8:9], v230 offset:25088
	v_add_f32_e32 v2, v96, v97
	v_add_f32_e32 v2, v98, v2
	v_add_f32_e32 v2, v99, v2
	v_add_f32_e32 v2, v100, v2
	v_add_f32_e32 v11, v101, v2
	v_cvt_pk_bf16_f32 v168, v96, v97
	v_cvt_pk_bf16_f32 v169, v98, v99
	ds_read_b64_tr_b16 v[2:3], v230 offset:28672
	ds_read_b64_tr_b16 v[4:5], v230 offset:29184
	s_waitcnt lgkmcnt(11)
	v_mfma_f32_32x32x16_bf16 v[128:143], v[204:207], v[172:175], v[128:143]
	v_add_f32_e32 v10, v210, v10
	v_fma_f32 v112, 0, v224, v10
	v_add_f32_e32 v113, v224, v10
	v_fma_f32 v114, v224, s6, v10
	v_fma_f32 v115, v225, s7, v10
	v_fma_f32 v117, v225, s9, v10
	v_fma_f32 v116, v224, s8, v10
	v_fma_f32 v119, v225, s11, v10
	v_fma_f32 v118, v224, s10, v10
	v_fma_f32 v121, v225, s13, v10
	v_fma_f32 v120, v224, s12, v10
	v_fma_f32 v123, v225, s15, v10
	v_fma_f32 v122, v224, s14, v10
	v_fma_f32 v125, v225, s17, v10
	v_fma_f32 v124, v224, s16, v10
	v_fma_f32 v127, v225, s19, v10
	v_fma_f32 v126, v224, s18, v10
	s_waitcnt lgkmcnt(10)
	s_nop 0
	v_mfma_f32_32x32x16_bf16 v[112:127], v[200:203], v[172:175], v[112:127]
	v_add_f32_e32 v10, v102, v11
	v_add_f32_e32 v10, v103, v10
	v_add_f32_e32 v10, v104, v10
	v_add_f32_e32 v14, v105, v10
	v_cvt_pk_bf16_f32 v170, v100, v101
	v_cvt_pk_bf16_f32 v171, v102, v103
	ds_read_b64_tr_b16 v[10:11], v230 offset:25600
	ds_read_b64_tr_b16 v[12:13], v230 offset:26112
	s_waitcnt lgkmcnt(11)
	v_mfma_f32_32x32x16_bf16 v[128:143], v[196:199], v[160:163], v[128:143]
	v_add_f32_e32 v14, v106, v14
	v_add_f32_e32 v14, v107, v14
	v_add_f32_e32 v14, v108, v14
	v_add_f32_e32 v14, v109, v14
	v_cvt_pk_bf16_f32 v164, v104, v105
	v_cvt_pk_bf16_f32 v165, v106, v107
	ds_read_b64_tr_b16 v[96:97], v230 offset:29696
	ds_read_b64_tr_b16 v[98:99], v230 offset:30208
	s_waitcnt lgkmcnt(12)
	v_mfma_f32_32x32x16_bf16 v[112:127], v[192:195], v[160:163], v[112:127]
	v_add_f32_e32 v14, v110, v14
	v_add_f32_e32 v14, v111, v14
	v_add_f32_e32 v14, v80, v14
	v_add_f32_e32 v14, v81, v14
	v_cvt_pk_bf16_f32 v166, v108, v109
	v_cvt_pk_bf16_f32 v167, v110, v111
	ds_read_b64_tr_b16 v[100:101], v230 offset:26624
	ds_read_b64_tr_b16 v[102:103], v230 offset:27136
	s_waitcnt lgkmcnt(13)
	v_mfma_f32_32x32x16_bf16 v[128:143], v[188:191], v[148:151], v[128:143]
	v_add_f32_e32 v14, v82, v14
	v_add_f32_e32 v14, v83, v14
	v_add_f32_e32 v14, v84, v14
	v_add_f32_e32 v14, v85, v14
	v_cvt_pk_bf16_f32 v156, v80, v81
	v_cvt_pk_bf16_f32 v157, v82, v83
	ds_read_b64_tr_b16 v[80:81], v230 offset:30720
	ds_read_b64_tr_b16 v[82:83], v230 offset:31232
	s_waitcnt lgkmcnt(14)
	v_mfma_f32_32x32x16_bf16 v[112:127], v[184:187], v[148:151], v[112:127]
	v_add_f32_e32 v14, v86, v14
	v_add_f32_e32 v14, v87, v14
	v_add_f32_e32 v14, v88, v14
	v_add_f32_e32 v14, v89, v14
	v_cvt_pk_bf16_f32 v158, v84, v85
	v_cvt_pk_bf16_f32 v159, v86, v87
	ds_read_b64_tr_b16 v[84:85], v230 offset:27648
	ds_read_b64_tr_b16 v[86:87], v230 offset:28160
	s_waitcnt lgkmcnt(14)
	v_mfma_f32_32x32x16_bf16 v[128:143], v[180:183], v[144:147], v[128:143]
	v_add_f32_e32 v14, v90, v14
	v_add_f32_e32 v14, v91, v14
	v_add_f32_e32 v14, v92, v14
	v_add_f32_e32 v14, v93, v14
	v_cvt_pk_bf16_f32 v152, v88, v89
	v_cvt_pk_bf16_f32 v153, v90, v91
	ds_read_b64_tr_b16 v[88:89], v230 offset:31744
	ds_read_b64_tr_b16 v[90:91], v230 offset:32256
	v_mfma_f32_32x32x16_bf16 v[112:127], v[176:179], v[144:147], v[112:127]
	v_add_f32_e32 v14, v94, v14
	v_add_f32_e32 v14, v95, v14
	v_add_f32_e32 v15, 0, v14
	v_cvt_pk_bf16_f32 v154, v92, v93
	v_cvt_pk_bf16_f32 v155, v94, v95
	s_add_i32 s22, s91, 1
	s_cmp_ge_i32 s22, s83
	s_cselect_b64 s[94:95], -1, 0
	s_and_b64 vcc, exec, s[94:95]
	s_cbranch_vccnz .LBB0_343
	v_mad_u64_u32 v[92:93], s[22:23], s22, v245, v[226:227]
	s_add_i32 s22, s80, s82
	s_mov_b32 s23, m0
	s_mov_b32 m0, s22
	s_nop 0
	global_load_lds_dwordx4 v[92:93], off
	s_mov_b32 m0, s23

;   #define RESC() do{ if(resc){ asm volatile("s_waitcnt lgkmcnt(0)":::"memory"); \
;       _Pragma("unroll") for(int d_=0;d_<4;++d_) _Pragma("unroll") for(int r=0;r<16;++r)o[d_][r]*=wsf[crow(r,hi)]; } }while(0)
;   #define ROT() do{sl_prev=sl_cur;sl_cur=sl_next;sl_next=(sl_next==(NSLOT-1)*SLOTB)?0:sl_next+SLOTB;}while(0)
;   #define ENDW(tt) do{ if((tt)+3<NT){WAIT_BAR(3);} else if((tt)+2<NT){WAIT_BAR(2);} else {WAIT_BAR(0);} }while(0)
; template<int THRL> __device__ __forceinline__ void attn_unit(int b,int qb,int T0,const bf16*Q,const bf16*__restrict__ K,const bf16*__restrict__ V,float*Dg,float cs,float lam,char*shm){
;     ...
;   for(;t+1<NT;t+=2){
;     STEP(pB0,pB1,pA0,pA1,t,(t+3<NT),(t+1<NT),(t+1<NT));       ENDW(t);   RESC(); ROT();
;     STEP(pA0,pA1,pB0,pB1,t+1,(t+4<NT),(t+2<NT),(t+2<NT));     ENDW(t+1); RESC(); ROT();
.LBB0_354:
	s_add_i32 s48, s48, 64
	v_cvt_f32_u32_e32 v2, s48
	v_fma_f32 v2, v224, v2, v208
	v_sub_f32_e32 v10, v2, v238
	v_fma_f32 v96, 0, v224, v10
	v_add_f32_e32 v97, v224, v10
	v_fma_f32 v99, v225, s7, v10
	v_fma_f32 v98, v224, s6, v10
	v_fma_f32 v101, v225, s9, v10
	v_fma_f32 v100, v224, s8, v10
	v_fma_f32 v103, v225, s11, v10
	v_fma_f32 v102, v224, s10, v10
	v_fma_f32 v105, v225, s13, v10
	v_fma_f32 v104, v224, s12, v10
	v_fma_f32 v107, v225, s15, v10
	v_fma_f32 v106, v224, s14, v10
	v_fma_f32 v109, v225, s17, v10
	v_fma_f32 v108, v224, s16, v10
	v_fma_f32 v111, v225, s19, v10
	v_fma_f32 v110, v224, s18, v10
	s_lshl_b32 s22, s80, 1
	v_add_u32_e32 v230, s22, v211
	ds_read_b64_tr_b16 v[6:7], v230 offset:24576
	ds_read_b64_tr_b16 v[8:9], v230 offset:25088
	v_add_f32_e32 v2, v128, v129
	v_add_f32_e32 v2, v130, v2
	v_add_f32_e32 v2, v131, v2
	v_add_f32_e32 v2, v132, v2
	v_add_f32_e32 v11, v133, v2
	v_cvt_pk_bf16_f32 v168, v128, v129
	v_cvt_pk_bf16_f32 v169, v130, v131
	ds_read_b64_tr_b16 v[2:3], v230 offset:28672
	ds_read_b64_tr_b16 v[4:5], v230 offset:29184
	s_waitcnt lgkmcnt(11)
	v_mfma_f32_32x32x16_bf16 v[96:111], v[204:207], v[172:175], v[96:111]
	v_add_f32_e32 v10, v210, v10
	v_fma_f32 v80, 0, v224, v10
	v_add_f32_e32 v81, v224, v10
	v_fma_f32 v82, v224, s6, v10
	v_fma_f32 v83, v225, s7, v10
	v_fma_f32 v85, v225, s9, v10
	v_fma_f32 v84, v224, s8, v10
	v_fma_f32 v87, v225, s11, v10
	v_fma_f32 v86, v224, s10, v10
	v_fma_f32 v89, v225, s13, v10
	v_fma_f32 v88, v224, s12, v10
	v_fma_f32 v91, v225, s15, v10
	v_fma_f32 v90, v224, s14, v10
	v_fma_f32 v93, v225, s17, v10
	v_fma_f32 v92, v224, s16, v10
	v_fma_f32 v95, v225, s19, v10
	v_fma_f32 v94, v224, s18, v10
	s_waitcnt lgkmcnt(10)
	s_nop 0
	v_mfma_f32_32x32x16_bf16 v[80:95], v[200:203], v[172:175], v[80:95]
	v_add_f32_e32 v10, v134, v11
	v_add_f32_e32 v10, v135, v10
	v_add_f32_e32 v10, v136, v10
	v_add_f32_e32 v128, v137, v10
	v_cvt_pk_bf16_f32 v170, v132, v133
	v_cvt_pk_bf16_f32 v171, v134, v135
	ds_read_b64_tr_b16 v[10:11], v230 offset:25600
	ds_read_b64_tr_b16 v[12:13], v230 offset:26112
	s_waitcnt lgkmcnt(11)
	v_mfma_f32_32x32x16_bf16 v[96:111], v[196:199], v[160:163], v[96:111]
	v_add_f32_e32 v128, v138, v128
	v_add_f32_e32 v128, v139, v128
	v_add_f32_e32 v128, v140, v128
	v_add_f32_e32 v132, v141, v128
	v_cvt_pk_bf16_f32 v164, v136, v137
	v_cvt_pk_bf16_f32 v165, v138, v139
	ds_read_b64_tr_b16 v[128:129], v230 offset:29696
	ds_read_b64_tr_b16 v[130:131], v230 offset:30208
	s_waitcnt lgkmcnt(12)
	v_mfma_f32_32x32x16_bf16 v[80:95], v[192:195], v[160:163], v[80:95]
	v_add_f32_e32 v132, v142, v132
	v_add_f32_e32 v132, v143, v132
	v_add_f32_e32 v132, v112, v132
	v_add_f32_e32 v136, v113, v132
	v_cvt_pk_bf16_f32 v166, v140, v141
	v_cvt_pk_bf16_f32 v167, v142, v143
	ds_read_b64_tr_b16 v[132:133], v230 offset:26624
	ds_read_b64_tr_b16 v[134:135], v230 offset:27136
	s_waitcnt lgkmcnt(13)
	v_mfma_f32_32x32x16_bf16 v[96:111], v[188:191], v[148:151], v[96:111]
	v_add_f32_e32 v136, v114, v136
	v_add_f32_e32 v136, v115, v136
	v_add_f32_e32 v136, v116, v136
	v_add_f32_e32 v136, v117, v136
	v_cvt_pk_bf16_f32 v156, v112, v113
	v_cvt_pk_bf16_f32 v157, v114, v115
	ds_read_b64_tr_b16 v[112:113], v230 offset:30720
	ds_read_b64_tr_b16 v[114:115], v230 offset:31232
	s_waitcnt lgkmcnt(14)
	v_mfma_f32_32x32x16_bf16 v[80:95], v[184:187], v[148:151], v[80:95]
	v_add_f32_e32 v136, v118, v136
	v_add_f32_e32 v136, v119, v136
	v_add_f32_e32 v136, v120, v136
	v_add_f32_e32 v136, v121, v136
	v_cvt_pk_bf16_f32 v158, v116, v117
	v_cvt_pk_bf16_f32 v159, v118, v119
	ds_read_b64_tr_b16 v[116:117], v230 offset:27648
	ds_read_b64_tr_b16 v[118:119], v230 offset:28160
	s_waitcnt lgkmcnt(14)
	v_mfma_f32_32x32x16_bf16 v[96:111], v[180:183], v[144:147], v[96:111]
	v_add_f32_e32 v136, v122, v136
	v_add_f32_e32 v136, v123, v136
	v_add_f32_e32 v136, v124, v136
	v_add_f32_e32 v136, v125, v136
	v_cvt_pk_bf16_f32 v152, v120, v121
	v_cvt_pk_bf16_f32 v153, v122, v123
	ds_read_b64_tr_b16 v[120:121], v230 offset:31744
	ds_read_b64_tr_b16 v[122:123], v230 offset:32256
	v_mfma_f32_32x32x16_bf16 v[80:95], v[176:179], v[144:147], v[80:95]
	v_add_f32_e32 v136, v126, v136
	v_add_f32_e32 v136, v127, v136
	v_add_f32_e32 v136, 0, v136
	v_cvt_pk_bf16_f32 v154, v124, v125
	v_cvt_pk_bf16_f32 v155, v126, v127
	s_add_i32 s22, s91, 2
	s_cmp_ge_i32 s22, s83
	s_cselect_b64 s[58:59], -1, 0
	s_and_b64 vcc, exec, s[58:59]
	s_cbranch_vccnz .LBB0_356
	v_mad_u64_u32 v[124:125], s[34:35], s22, v245, v[226:227]
	s_add_i32 s23, s87, s82
	s_mov_b32 s34, m0
	s_mov_b32 m0, s23
	s_nop 0
	global_load_lds_dwordx4 v[124:125], off
	s_mov_b32 m0, s34

;   #define RESC() do{ if(resc){ asm volatile("s_waitcnt lgkmcnt(0)":::"memory"); \
;       _Pragma("unroll") for(int d_=0;d_<4;++d_) _Pragma("unroll") for(int r=0;r<16;++r)o[d_][r]*=wsf[crow(r,hi)]; } }while(0)
; template<int THRL> __device__ __forceinline__ void attn_unit(int b,int qb,int T0,const bf16*Q,const bf16*__restrict__ K,const bf16*__restrict__ V,float*Dg,float cs,float lam,char*shm){
;     ...
;   STEP(pB0,pB1,pA0,pA1,NT-1,false,false,false); RESC();
.LBB0_389:
	s_lshl_b32 s22, s83, 6
	s_sub_i32 s22, s22, 64
	v_cvt_f32_i32_e32 v0, s22
	v_fmac_f32_e32 v208, v224, v0
	v_sub_f32_e32 v10, v208, v238
	v_fma_f32 v112, 0, v224, v10
	v_add_f32_e32 v113, v224, v10
	v_fma_f32 v115, v225, s7, v10
	v_fma_f32 v114, v224, s6, v10
	v_fma_f32 v117, v225, s9, v10
	v_fma_f32 v116, v224, s8, v10
	v_fma_f32 v119, v225, s11, v10
	v_fma_f32 v118, v224, s10, v10
	v_fma_f32 v121, v225, s13, v10
	v_fma_f32 v120, v224, s12, v10
	v_fma_f32 v123, v225, s15, v10
	v_fma_f32 v122, v224, s14, v10
	v_fma_f32 v125, v225, s17, v10
	v_fma_f32 v124, v224, s16, v10
	v_fma_f32 v127, v225, s19, v10
	v_fma_f32 v126, v224, s18, v10
	v_add_u32_e32 v0, s90, v211
	ds_read_b64_tr_b16 v[6:7], v0 offset:24576
	ds_read_b64_tr_b16 v[8:9], v0 offset:25088
	v_add_f32_e32 v2, v96, v97
	v_add_f32_e32 v2, v98, v2
	v_add_f32_e32 v2, v99, v2
	v_add_f32_e32 v2, v100, v2
	v_add_f32_e32 v11, v101, v2
	v_cvt_pk_bf16_f32 v168, v96, v97
	v_cvt_pk_bf16_f32 v169, v98, v99
	ds_read_b64_tr_b16 v[2:3], v0 offset:28672
	ds_read_b64_tr_b16 v[4:5], v0 offset:29184
	v_add_f32_e32 v10, v210, v10
	v_fma_f32 v128, 0, v224, v10
	v_add_f32_e32 v129, v224, v10
	v_fma_f32 v131, v225, s7, v10
	v_fma_f32 v130, v224, s6, v10
	v_fma_f32 v133, v225, s9, v10
	v_fma_f32 v132, v224, s8, v10
	v_fma_f32 v135, v225, s11, v10
	v_fma_f32 v134, v224, s10, v10
	v_fma_f32 v137, v225, s13, v10
	v_fma_f32 v136, v224, s12, v10
	v_fma_f32 v139, v225, s15, v10
	v_fma_f32 v138, v224, s14, v10
	v_fma_f32 v141, v225, s17, v10
	v_fma_f32 v140, v224, s16, v10
	v_fma_f32 v143, v225, s19, v10
	v_fma_f32 v142, v224, s18, v10
	s_waitcnt lgkmcnt(11)
	v_mfma_f32_32x32x16_bf16 v[112:127], v[204:207], v[172:175], v[112:127]
	v_add_f32_e32 v10, v102, v11
	v_add_f32_e32 v10, v103, v10
	v_add_f32_e32 v10, v104, v10
	v_add_f32_e32 v14, v105, v10
	v_cvt_pk_bf16_f32 v170, v100, v101
	v_cvt_pk_bf16_f32 v171, v102, v103
	s_waitcnt lgkmcnt(10)
	v_mfma_f32_32x32x16_bf16 v[128:143], v[200:203], v[172:175], v[128:143]
	ds_read_b64_tr_b16 v[10:11], v0 offset:25600
	ds_read_b64_tr_b16 v[12:13], v0 offset:26112
	v_add_f32_e32 v14, v106, v14
	v_add_f32_e32 v14, v107, v14
	v_add_f32_e32 v14, v108, v14
	v_add_f32_e32 v14, v109, v14
	v_cvt_pk_bf16_f32 v164, v104, v105
	v_cvt_pk_bf16_f32 v165, v106, v107
	s_waitcnt lgkmcnt(11)
	v_mfma_f32_32x32x16_bf16 v[112:127], v[196:199], v[160:163], v[112:127]
	ds_read_b64_tr_b16 v[172:173], v0 offset:29696
	ds_read_b64_tr_b16 v[174:175], v0 offset:30208
	v_add_f32_e32 v14, v110, v14
	v_add_f32_e32 v14, v111, v14
	v_add_f32_e32 v14, v80, v14
	v_add_f32_e32 v14, v81, v14
	v_cvt_pk_bf16_f32 v166, v108, v109
	v_cvt_pk_bf16_f32 v167, v110, v111
	s_waitcnt lgkmcnt(12)
	v_mfma_f32_32x32x16_bf16 v[128:143], v[192:195], v[160:163], v[128:143]
	ds_read_b64_tr_b16 v[160:161], v0 offset:26624
	ds_read_b64_tr_b16 v[162:163], v0 offset:27136
	v_add_f32_e32 v14, v82, v14
	v_add_f32_e32 v14, v83, v14
	v_add_f32_e32 v14, v84, v14
	v_add_f32_e32 v14, v85, v14
	v_cvt_pk_bf16_f32 v156, v80, v81
	v_cvt_pk_bf16_f32 v157, v82, v83
	s_waitcnt lgkmcnt(13)
	v_mfma_f32_32x32x16_bf16 v[112:127], v[188:191], v[148:151], v[112:127]
	ds_read_b64_tr_b16 v[188:189], v0 offset:30720
	ds_read_b64_tr_b16 v[190:191], v0 offset:31232
	v_add_f32_e32 v14, v86, v14
	v_add_f32_e32 v14, v87, v14
	v_add_f32_e32 v14, v88, v14
	v_add_f32_e32 v14, v89, v14
	v_cvt_pk_bf16_f32 v158, v84, v85
	v_cvt_pk_bf16_f32 v159, v86, v87
	s_waitcnt lgkmcnt(14)
	v_mfma_f32_32x32x16_bf16 v[128:143], v[184:187], v[148:151], v[128:143]
	ds_read_b64_tr_b16 v[148:149], v0 offset:27648
	ds_read_b64_tr_b16 v[150:151], v0 offset:28160
	v_add_f32_e32 v14, v90, v14
	v_add_f32_e32 v14, v91, v14
	v_add_f32_e32 v14, v92, v14
	v_add_f32_e32 v14, v93, v14
	v_cvt_pk_bf16_f32 v152, v88, v89
	v_cvt_pk_bf16_f32 v153, v90, v91
	s_waitcnt lgkmcnt(14)
; __device__ __forceinline__ void cmask(f32x16&p0,f32x16&p1,int jb,int qrel,int hi){
;   const float NEG=-INFINITY; int kb=64*jb+4*hi;
;   #pragma unroll
;   for(int r=0;r<16;++r){int kv=kb+(r&3)+8*(r>>2); if(kv>qrel)p0[r]=NEG; if(kv+32>qrel)p1[r]=NEG;}
; }
	v_mfma_f32_32x32x16_bf16 v[112:127], v[180:183], v[144:147], v[112:127]
	ds_read_b64_tr_b16 v[180:181], v0 offset:31744
	ds_read_b64_tr_b16 v[182:183], v0 offset:32256
	v_add_f32_e32 v14, v94, v14
	v_add_f32_e32 v14, v95, v14
	v_add_f32_e32 v14, 0, v14
	v_cvt_pk_bf16_f32 v154, v92, v93
	v_cvt_pk_bf16_f32 v155, v94, v95
	v_mfma_f32_32x32x16_bf16 v[128:143], v[176:179], v[144:147], v[128:143]
	v_or_b32_e32 v80, 0xe0, v250
	v_or_b32_e32 v15, 0xc0, v250
	v_cmp_le_i32_e32 vcc, v80, v233
	v_add_f32_e32 v14, v239, v14
	s_nop 7
	v_cndmask_b32_e32 v80, v244, v128, vcc
	v_cmp_lt_i32_e32 vcc, v15, v233
	s_nop 1
	v_cndmask_b32_e32 v97, v244, v113, vcc
	v_cmp_le_i32_e32 vcc, v15, v233
	v_or_b32_e32 v15, 0xe1, v250
	s_nop 0
	v_cndmask_b32_e32 v96, v244, v112, vcc
	v_cmp_le_i32_e32 vcc, v15, v233
	v_or_b32_e32 v15, 0xc2, v250
	v_max_f32_e32 v112, v96, v96
	v_cndmask_b32_e32 v81, v244, v129, vcc
	v_cmp_le_i32_e32 vcc, v15, v233
	v_or_b32_e32 v15, 0xe2, v250
	s_nop 0
	v_cndmask_b32_e32 v98, v244, v114, vcc
	v_cmp_le_i32_e32 vcc, v15, v233
	v_or_b32_e32 v15, 0xc3, v250
	s_nop 0
	v_cndmask_b32_e32 v82, v244, v130, vcc
	v_cmp_le_i32_e32 vcc, v15, v233
	v_or_b32_e32 v15, 0xe3, v250
	s_nop 0
	v_cndmask_b32_e32 v99, v244, v115, vcc
	v_cmp_le_i32_e32 vcc, v15, v233
	v_or_b32_e32 v15, 0xc8, v250
	s_nop 0
	v_cndmask_b32_e32 v83, v244, v131, vcc
	v_cmp_le_i32_e32 vcc, v15, v233
	v_or_b32_e32 v15, 0xe8, v250
	s_nop 0
	v_cndmask_b32_e32 v100, v244, v116, vcc
	v_cmp_le_i32_e32 vcc, v15, v233
	v_or_b32_e32 v15, 0xc9, v250
	s_nop 0
	v_cndmask_b32_e32 v84, v244, v132, vcc
	v_cmp_le_i32_e32 vcc, v15, v233
	v_or_b32_e32 v15, 0xe9, v250
	s_nop 0
	v_cndmask_b32_e32 v101, v244, v117, vcc
	v_cmp_le_i32_e32 vcc, v15, v233
	v_or_b32_e32 v15, 0xca, v250
	s_nop 0
	v_cndmask_b32_e32 v85, v244, v133, vcc
	v_cmp_le_i32_e32 vcc, v15, v233
	v_or_b32_e32 v15, 0xea, v250
	s_nop 0
	v_cndmask_b32_e32 v102, v244, v118, vcc
	v_cmp_le_i32_e32 vcc, v15, v233
	v_or_b32_e32 v15, 0xcb, v250
	s_nop 0
	v_cndmask_b32_e32 v86, v244, v134, vcc
	v_cmp_le_i32_e32 vcc, v15, v233
	v_or_b32_e32 v15, 0xeb, v250
	s_nop 0
	v_cndmask_b32_e32 v103, v244, v119, vcc
	v_cmp_le_i32_e32 vcc, v15, v233
	v_or_b32_e32 v15, 0xd0, v250
	s_nop 0
	v_cndmask_b32_e32 v87, v244, v135, vcc
	v_cmp_le_i32_e32 vcc, v15, v233
	v_or_b32_e32 v15, 0xf0, v250
	s_nop 0
	v_cndmask_b32_e32 v104, v244, v120, vcc
	v_cmp_le_i32_e32 vcc, v15, v233
	v_or_b32_e32 v15, 0xd1, v250
	s_nop 0
	v_cndmask_b32_e32 v88, v244, v136, vcc
	v_cmp_le_i32_e32 vcc, v15, v233
	v_or_b32_e32 v15, 0xf1, v250
	s_nop 0
	v_cndmask_b32_e32 v105, v244, v121, vcc
	v_cmp_le_i32_e32 vcc, v15, v233
	v_or_b32_e32 v15, 0xd2, v250
	s_nop 0
	v_cndmask_b32_e32 v89, v244, v137, vcc
	v_cmp_le_i32_e32 vcc, v15, v233
	v_or_b32_e32 v15, 0xf2, v250
	s_nop 0
	v_cndmask_b32_e32 v106, v244, v122, vcc
	v_cmp_le_i32_e32 vcc, v15, v233
	v_or_b32_e32 v15, 0xd3, v250
	s_nop 0
	v_cndmask_b32_e32 v90, v244, v138, vcc
	v_cmp_le_i32_e32 vcc, v15, v233
	v_or_b32_e32 v15, 0xf3, v250
	s_nop 0
	v_cndmask_b32_e32 v107, v244, v123, vcc
	v_cmp_le_i32_e32 vcc, v15, v233
	v_or_b32_e32 v15, 0xd8, v250
	s_nop 0
	v_cndmask_b32_e32 v91, v244, v139, vcc
	v_cmp_le_i32_e32 vcc, v15, v233
	v_or_b32_e32 v15, 0xf8, v250
	s_nop 0
	v_cndmask_b32_e32 v108, v244, v124, vcc
	v_cmp_le_i32_e32 vcc, v15, v233
	v_or_b32_e32 v15, 0xd9, v250
	s_nop 0
	v_cndmask_b32_e32 v92, v244, v140, vcc
	v_cmp_le_i32_e32 vcc, v15, v233
	v_or_b32_e32 v15, 0xf9, v250
	s_nop 0
	v_cndmask_b32_e32 v109, v244, v125, vcc
	v_cmp_le_i32_e32 vcc, v15, v233
	v_or_b32_e32 v15, 0xda, v250
	s_nop 0
	v_cndmask_b32_e32 v93, v244, v141, vcc
	v_cmp_le_i32_e32 vcc, v15, v233
	v_or_b32_e32 v15, 0xfa, v250
	s_nop 0
	v_cndmask_b32_e32 v110, v244, v126, vcc
	v_cmp_le_i32_e32 vcc, v15, v233
	v_or_b32_e32 v15, 0xdb, v250
	s_nop 0
	v_cndmask_b32_e32 v94, v244, v142, vcc
	v_cmp_le_i32_e32 vcc, v15, v233
	v_or_b32_e32 v15, 0xfb, v250
	s_nop 0
	v_cndmask_b32_e32 v111, v244, v127, vcc
	v_cmp_le_i32_e32 vcc, v15, v233
	v_max_f32_e32 v15, v97, v97
	v_max_f32_e32 v15, v112, v15
	v_max3_f32 v112, v98, v99, v81
	v_max3_f32 v15, v15, v80, v82
	v_max3_f32 v15, v15, v83, v100
	v_max3_f32 v112, v112, v102, v103
	v_max3_f32 v15, v15, v101, v84
	v_max3_f32 v112, v112, v86, v87
	v_max3_f32 v15, v15, v85, v104
	v_max3_f32 v112, v112, v106, v107
	v_max3_f32 v15, v15, v105, v88
	v_max3_f32 v112, v112, v90, v91
	v_cndmask_b32_e32 v95, v244, v143, vcc
	v_max3_f32 v15, v15, v89, v108
	v_max3_f32 v112, v112, v110, v111
	v_max3_f32 v15, v15, v109, v92
	v_max3_f32 v112, v112, v94, v95
	v_max3_f32 v15, v15, v93, v112
	v_mov_b32_e32 v112, v15
	s_nop 1
	v_permlane32_swap_b32_e32 v15, v112
	v_max_f32_e32 v112, v112, v112
	v_max_f32_e32 v15, v15, v15
	v_max_f32_e32 v15, v15, v112
	v_cmp_lt_f32_e32 vcc, s69, v15
	s_cmp_lg_u64 vcc, 0
	s_cselect_b64 s[34:35], -1, 0
	s_cbranch_vccnz .LBB0_394
